# v33 staggered 4-buffer DMA attention plus static s_setprio 1 for the trailing half (waves 4-7) inside the KV loop
# baseline (speedup 1.0000x reference)
; __device__ __forceinline__ int opaque_tid() { int t = (int)threadIdx.x; asm volatile("" : "+v"(t)); return t; }
; __device__ __forceinline__ int v_st(int k, int c) { const int kk = (k & ~0xC) | ((k & 4) << 1) | ((k & 8) >> 1); return ((kk >> 3) * 4 + (c >> 5)) * 512 + ((kk & 7) * 32 + (c & 31)) * 2; }
; __device__ __forceinline__ int v_rd_base(int lane) { return ((lane & 3) << 3) | (((lane >> 2) & 3) << 6) | (((lane >> 4) & 1) << 5) | (((lane >> 5) & 1) << 8); }
; #define SLOAD(i, k0) do { sr_[i].vs0 = St::ld8(&Vh[(long)((k0) + sr) * LDK + sc]); sr_[i].vs1 = St::ld8(&Vh[(long)((k0) + 32 + sr) * LDK + sc]); \
;     sr_[i].ks0 = St::ld8(&Kh[(long)((k0) + sr) * LDK + sc]); sr_[i].ks1 = St::ld8(&Kh[(long)((k0) + 32 + sr) * LDK + sc]); } while (0)
; #define SWAIT() do { if constexpr (SDEPTH == 2) asm volatile("s_waitcnt vmcnt(4)" ::: "memory"); else asm volatile("s_waitcnt vmcnt(0)" ::: "memory"); } while (0)
; template <typename TQ>
; __device__ __forceinline__ void attn_dense_body(const TQ* __restrict__ Qb, const bf16* __restrict__ Kh, const bf16* __restrict__ Vh,
;                                                 unsigned short* __restrict__ Ob, int seq, char* lds) {
;     ...
;   const int tid = ::opaque_tid(), wid = tid >> 6, lane = tid & 63, r32 = lane & 31, hi = lane >> 5;
;   bf16* V_lds = (bf16*)lds; bf16* K_lds = (bf16*)(lds + 2 * SHM_V);
;   float* ws = (float*)(lds + 2 * SHM_V + 2 * SHM_K) + wid * 64; float* li_l = ws; float* al_l = ws + 32;
;   float m_reg = -1e30f, l_reg = 0; f32x16 o[4] = {}; bf16x8 qr[8];
;   const TQ* Qw = Qb + (long)(wid * QBLK + r32) * LDQ + hi * 8;
; #pragma unroll
;   for (int d0 = 0; d0 < 8; ++d0) qr[d0] = SQ::tobf(SQ::ld8(Qw + d0 * 16));
;   const int sr = tid >> 4, sc = (tid & 15) * 8, vst0 = v_st(sr, sc), vst1 = v_st(32 + sr, sc);
;   const int vb0 = (int)(uintptr_t)V_lds + v_rd_base(lane);
;   struct { typename St::T vs0, vs1, ks0, ks1; } sr_[SDEPTH];
;     ...
;   f32x16 pA0, pA1, pB0, pB1; float mnA, mnB, alA, alB; bf16x8 pa0, pa1, pa2, pa3; const int NT = seq / KVBLK;
;   constexpr int SE = 0, SO = SDEPTH - 1;
;   SLOAD(SE, 0); asm volatile("s_waitcnt vmcnt(0)" ::: "memory"); SWRITE(0, SE); __syncthreads();
;   qkt(pA0, pA1, K_lds, qr, r32, hi); partialSM(pA0, pA1, m_reg, mnA, alA);
;   SLOAD(SO, KVBLK); if constexpr (SDEPTH == 2) { if (2 < NT) SLOAD(SE, 2 * KVBLK); }
;   SWAIT(); SWRITE(1, SO); __syncthreads();
.LBB0_75:
	s_lshl_b64 s[40:41], s[0:1], 1
	v_readlane_b32 s0, v254, 41
	v_readlane_b32 s1, v254, 42
	s_add_u32 s46, s0, s40
	v_mov_b32_e32 v74, v211
	s_addc_u32 s47, s1, s41
	s_lshl_b64 s[0:1], s[38:39], 1
	s_add_u32 s38, s58, s0
	v_ashrrev_i32_e32 v16, 4, v74
	v_lshlrev_b32_e32 v22, 3, v74
	v_add_u32_e32 v18, 32, v16
	s_addc_u32 s39, s59, s1
	v_and_b32_e32 v176, 0x78, v22
	v_ashrrev_i32_e32 v17, 31, v16
	v_ashrrev_i32_e32 v19, 31, v18
	s_add_u32 s42, s24, s0
	v_lshlrev_b32_e32 v23, 1, v176
	v_lshlrev_b64 v[48:49], 8, v[16:17]
	v_lshlrev_b64 v[8:9], 8, v[18:19]
	s_addc_u32 s43, s25, s1
	s_mov_b64 s[6:7], s[38:39]
	s_mov_b64 s[68:69], s[42:43]
	v_or_b32_e32 v50, v48, v23
	v_mov_b32_e32 v51, v49
	v_or_b32_e32 v8, v8, v23
	v_ashrrev_i32_e32 v183, 6, v74
	s_waitcnt lgkmcnt(0)
	v_lshl_add_u64 v[0:1], s[42:43], 0, v[50:51]
	v_lshl_add_u64 v[4:5], s[42:43], 0, v[8:9]
	v_lshl_add_u64 v[10:11], s[38:39], 0, v[50:51]
	v_lshl_add_u64 v[12:13], s[38:39], 0, v[8:9]
	v_and_b32_e32 v179, 31, v74
	v_lshlrev_b32_e32 v178, 5, v183
	global_load_dwordx4 v[0:3], v[0:1], off
	s_nop 0
	global_load_dwordx4 v[4:7], v[4:5], off
	s_nop 0
	global_load_dwordx4 v[8:11], v[10:11], off
	s_nop 0
	global_load_dwordx4 v[12:15], v[12:13], off
	v_or_b32_e32 v20, v178, v179
	v_ashrrev_i32_e32 v21, 31, v20
	v_bfe_u32 v182, v74, 5, 1
	v_lshlrev_b64 v[20:21], 11, v[20:21]
	v_lshl_add_u64 v[20:21], s[46:47], 0, v[20:21]
	v_lshlrev_b32_e32 v208, 4, v182
	v_lshl_add_u64 v[20:21], v[20:21], 0, v[208:209]
	global_load_dwordx4 v[112:115], v[20:21], off
	global_load_dwordx4 v[108:111], v[20:21], off offset:32
	global_load_dwordx4 v[120:123], v[20:21], off offset:64
	global_load_dwordx4 v[124:127], v[20:21], off offset:96
	global_load_dwordx4 v[116:119], v[20:21], off offset:128
	global_load_dwordx4 v[104:107], v[20:21], off offset:160
	global_load_dwordx4 v[100:103], v[20:21], off offset:192
	global_load_dwordx4 v[96:99], v[20:21], off offset:224
	v_and_b32_e32 v19, 0xfffff0, v16
	v_lshlrev_b32_e32 v24, 1, v16
	v_lshrrev_b32_e32 v25, 1, v16
	v_and_b32_e32 v26, 3, v16
	v_and_or_b32 v19, v24, 8, v19
	v_and_or_b32 v24, v25, 4, v26
	v_and_b32_e32 v25, 0xfffff0, v18
	v_lshlrev_b32_e32 v26, 1, v18
	v_and_b32_e32 v17, 0x70, v74
	v_bfe_u32 v22, v22, 5, 2
	v_lshlrev_b32_e32 v16, 8, v16
	v_lshlrev_b32_e32 v18, 8, v18
	v_lshrrev_b32_e32 v19, 1, v19
	v_and_or_b32 v25, v26, 8, v25
	v_lshlrev_b32_e32 v52, 4, v74
	v_bitop3_b32 v16, v23, v16, v17 bitop3:0xde
	v_bitop3_b32 v17, v23, v18, v17 bitop3:0xde
	v_or_b32_e32 v18, v19, v22
	v_lshrrev_b32_e32 v19, 1, v25
	v_lshlrev_b32_e32 v68, 8, v179
	v_and_b32_e32 v69, 0x70, v52
	v_lshlrev_b32_e32 v24, 6, v24
	v_and_b32_e32 v28, 48, v23
	v_add_u32_e32 v189, 0, v16
	v_add_u32_e32 v190, 0, v17
	v_lshlrev_b32_e32 v16, 9, v18
	v_or_b32_e32 v17, v19, v22
	v_bitop3_b32 v27, v208, v68, v69 bitop3:0xde
	v_or3_b32 v16, v16, v24, v28
	v_lshlrev_b32_e32 v17, 9, v17
	v_or3_b32 v17, v17, v24, v28
	v_add_u32_e32 v191, 0, v16
	v_add_u32_e32 v193, 0, v27
	s_waitcnt vmcnt(0)
	v_add_u32_e32 v192, 0, v17
	s_mov_b64 s[28:29], 0x4000
	s_add_i32 s3, 0, 0x20800
	v_and_b32_e32 v71, 0xc0, v52
	v_and_b32_e32 v177, 63, v74
	v_lshlrev_b32_e32 v70, 3, v177
	s_mov_b32 s4, 0x42b504f3
	s_cmp_lg_u32 0, -1
	s_mov_b32 s72, s73
	s_mov_b32 s74, s73
	s_mov_b32 s75, s73
	s_waitcnt vmcnt(0)
	ds_write_b128 v191, v[0:3]
	s_waitcnt vmcnt(10)
	ds_write_b128 v192, v[4:7]
	s_waitcnt vmcnt(9)
	ds_write_b128 v189, v[8:11] offset:32768
	s_waitcnt vmcnt(8)
	ds_write_b128 v190, v[12:15] offset:32768
	s_waitcnt lgkmcnt(0)
	s_barrier
	ds_read_b128 v[0:3], v193 offset:32768
	ds_read_b128 v[4:7], v193 offset:40960
	s_waitcnt vmcnt(7) lgkmcnt(1)
	v_mfma_f32_32x32x16_bf16 v[16:31], v[0:3], v[112:115], 0
	v_or_b32_e32 v0, 32, v208
	v_bitop3_b32 v0, v0, v68, v69 bitop3:0xde
	v_add_u32_e32 v198, 0, v0
	v_and_b32_e32 v12, 0x3fffffc0, v74
	v_lshl_add_u64 v[8:9], v[50:51], 0, s[28:29]
	s_mov_b64 s[28:29], 0x6000
	v_lshl_add_u64 v[10:11], v[50:51], 0, s[28:29]
	s_waitcnt lgkmcnt(0)
	v_mfma_f32_32x32x16_bf16 v[32:47], v[4:7], v[112:115], 0
	ds_read_b128 v[0:3], v198 offset:32768
	ds_read_b128 v[4:7], v198 offset:40960
	v_lshl_add_u32 v184, v12, 2, s3
	v_lshl_add_u64 v[12:13], s[42:43], 0, v[8:9]
	v_lshl_add_u64 v[14:15], s[42:43], 0, v[10:11]
	s_mov_b64 s[28:29], 0x8000
	s_cselect_b32 s3, 0, 0
	s_mov_b32 s76, s73
	s_waitcnt vmcnt(6) lgkmcnt(1)
	v_mfma_f32_32x32x16_bf16 v[16:31], v[0:3], v[108:111], v[16:31]
	v_or_b32_e32 v0, 64, v208
	v_bitop3_b32 v0, v0, v68, v69 bitop3:0xde
	v_add_u32_e32 v197, 0, v0
	s_mov_b32 s77, s73
	s_mov_b32 s78, s73
	s_mov_b32 s79, s73
	s_mov_b32 s80, s73
	s_waitcnt lgkmcnt(0)
	v_mfma_f32_32x32x16_bf16 v[32:47], v[4:7], v[108:111], v[32:47]
	ds_read_b128 v[0:3], v197 offset:32768
	ds_read_b128 v[4:7], v197 offset:40960
	s_mov_b32 s81, s73
	s_mov_b32 s82, s73
	s_mov_b32 s83, s73
	s_mov_b32 s84, s73
	s_mov_b32 s85, s73
	s_mov_b32 s86, s73
	s_waitcnt vmcnt(5) lgkmcnt(1)
	v_mfma_f32_32x32x16_bf16 v[16:31], v[0:3], v[120:123], v[16:31]
	v_or_b32_e32 v0, 0x60, v208
	v_bitop3_b32 v0, v0, v68, v69 bitop3:0xde
	v_add_u32_e32 v196, 0, v0
	s_mov_b32 s87, s73
	v_lshl_add_u32 v185, v179, 2, v184
	v_mov_b32_e32 v186, 0
	s_waitcnt lgkmcnt(0)
	v_mfma_f32_32x32x16_bf16 v[32:47], v[4:7], v[120:123], v[32:47]
	ds_read_b128 v[0:3], v196 offset:32768
	ds_read_b128 v[4:7], v196 offset:40960
	s_waitcnt vmcnt(4) lgkmcnt(1)
	v_mfma_f32_32x32x16_bf16 v[16:31], v[0:3], v[124:127], v[16:31]
	v_or_b32_e32 v0, 0x80, v208
	v_bitop3_b32 v0, v0, v68, v69 bitop3:0xde
	v_add_u32_e32 v194, 0, v0
	ds_read_b128 v[0:3], v194 offset:32768
	s_waitcnt lgkmcnt(1)
	v_mfma_f32_32x32x16_bf16 v[32:47], v[4:7], v[124:127], v[32:47]
	ds_read_b128 v[4:7], v194 offset:40960
	s_waitcnt vmcnt(3) lgkmcnt(1)
; #define SLOAD(i, k0) do { sr_[i].vs0 = St::ld8(&Vh[(long)((k0) + sr) * LDK + sc]); sr_[i].vs1 = St::ld8(&Vh[(long)((k0) + 32 + sr) * LDK + sc]); \
;     sr_[i].ks0 = St::ld8(&Kh[(long)((k0) + sr) * LDK + sc]); sr_[i].ks1 = St::ld8(&Kh[(long)((k0) + 32 + sr) * LDK + sc]); } while (0)
; #define SWAIT() do { if constexpr (SDEPTH == 2) asm volatile("s_waitcnt vmcnt(4)" ::: "memory"); else asm volatile("s_waitcnt vmcnt(0)" ::: "memory"); } while (0)
; __device__ __forceinline__ void partialSM(f32x16& p0, f32x16& p1, float& m_reg, float& mn, float& alpha) {
;   constexpr float C = SCALE * 1.4426950408889634f;
;   float pmax = p0[0]; for (int r = 1; r < 16; ++r) pmax = fmaxf(pmax, p0[r]); for (int r = 0; r < 16; ++r) pmax = fmaxf(pmax, p1[r]);
;   { auto rr = __builtin_amdgcn_permlane32_swap(__float_as_uint(pmax), __float_as_uint(pmax), false, false);
;     pmax = fmaxf(__uint_as_float(rr[0]), __uint_as_float(rr[1])); }
;   if (__builtin_expect(__all(pmax - m_reg <= THR / SCALE), 1)) { mn = m_reg; alpha = 1.f; }
;   else { mn = fmaxf(m_reg, pmax); alpha = __builtin_amdgcn_exp2f((m_reg - mn) * C); m_reg = mn; }
;   float mnC = -mn * C;
;   for (int r = 0; r < 16; ++r) p0[r] = fmaf(p0[r], C, mnC); for (int r = 0; r < 16; ++r) p1[r] = fmaf(p1[r], C, mnC);
;   for (int r = 0; r < 16; ++r) p0[r] = __builtin_amdgcn_exp2f(p0[r]);
; template <typename TQ>
; __device__ __forceinline__ void attn_dense_body(const TQ* __restrict__ Qb, const bf16* __restrict__ Kh, const bf16* __restrict__ Vh,
;                                                 unsigned short* __restrict__ Ob, int seq, char* lds) {
;     ...
;   SLOAD(SE, 0); asm volatile("s_waitcnt vmcnt(0)" ::: "memory"); SWRITE(0, SE); __syncthreads();
;   qkt(pA0, pA1, K_lds, qr, r32, hi); partialSM(pA0, pA1, m_reg, mnA, alA);
;   SLOAD(SO, KVBLK); if constexpr (SDEPTH == 2) { if (2 < NT) SLOAD(SE, 2 * KVBLK); }
;   SWAIT(); SWRITE(1, SO); __syncthreads();
	v_mfma_f32_32x32x16_bf16 v[16:31], v[0:3], v[116:119], v[16:31]
	v_or_b32_e32 v0, 0xa0, v208
	v_bitop3_b32 v0, v0, v68, v69 bitop3:0xde
	v_add_u32_e32 v195, 0, v0
	ds_read_b128 v[0:3], v195 offset:32768
	s_waitcnt lgkmcnt(1)
	v_mfma_f32_32x32x16_bf16 v[32:47], v[4:7], v[116:119], v[32:47]
	ds_read_b128 v[4:7], v195 offset:40960
	global_load_dwordx4 v[52:55], v[12:13], off
	global_load_dwordx4 v[56:59], v[14:15], off
	s_waitcnt vmcnt(4) lgkmcnt(1)
	v_mfma_f32_32x32x16_bf16 v[16:31], v[0:3], v[104:107], v[16:31]
	v_lshl_add_u64 v[0:1], s[38:39], 0, v[8:9]
	v_lshl_add_u64 v[2:3], s[38:39], 0, v[10:11]
	global_load_dwordx4 v[60:63], v[0:1], off
	global_load_dwordx4 v[64:67], v[2:3], off
	v_or_b32_e32 v0, 0xc0, v208
	v_bitop3_b32 v0, v0, v68, v69 bitop3:0xde
	v_add_u32_e32 v200, 0, v0
	ds_read_b128 v[0:3], v200 offset:32768
	v_lshlrev_b32_e32 v9, 1, v74
	v_and_or_b32 v8, v70, 24, v71
	s_waitcnt lgkmcnt(1)
	v_mfma_f32_32x32x16_bf16 v[32:47], v[4:7], v[104:107], v[32:47]
	v_and_b32_e32 v4, 32, v9
	v_and_b32_e32 v5, 0x100, v70
	v_or3_b32 v75, v8, v4, v5
	ds_read_b128 v[4:7], v200 offset:40960
	v_add_u32_e32 v188, s3, v75
	s_waitcnt vmcnt(5) lgkmcnt(1)
	v_mfma_f32_32x32x16_bf16 v[16:31], v[0:3], v[100:103], v[16:31]
	v_or_b32_e32 v0, 0xe0, v208
	v_bitop3_b32 v0, v0, v68, v69 bitop3:0xde
	v_add_u32_e32 v199, 0, v0
	ds_read_b128 v[0:3], v199 offset:32768
	ds_read_b128 v[68:71], v199 offset:40960
	s_waitcnt lgkmcnt(2)
	v_mfma_f32_32x32x16_bf16 v[32:47], v[4:7], v[100:103], v[32:47]
	s_waitcnt vmcnt(4) lgkmcnt(1)
	v_mfma_f32_32x32x16_bf16 v[16:31], v[0:3], v[96:99], v[16:31]
	v_mov_b64_e32 v[0:1], s[72:73]
	v_mov_b64_e32 v[14:15], s[86:87]
	v_mov_b64_e32 v[2:3], s[74:75]
	v_mov_b64_e32 v[4:5], s[76:77]
	v_mov_b64_e32 v[6:7], s[78:79]
	v_mov_b64_e32 v[8:9], s[80:81]
	v_mov_b64_e32 v[10:11], s[82:83]
	s_waitcnt lgkmcnt(0)
	v_mfma_f32_32x32x16_bf16 v[32:47], v[68:71], v[96:99], v[32:47]
	s_nop 2
	v_max_f32_e32 v68, v17, v17
	v_max_f32_e32 v69, v16, v16
	v_max_f32_e32 v68, v69, v68
	v_max3_f32 v68, v68, v18, v19
	v_max3_f32 v68, v68, v20, v21
	v_max3_f32 v68, v68, v22, v23
	v_max3_f32 v68, v68, v24, v25
	v_max3_f32 v68, v68, v26, v27
	v_max3_f32 v68, v68, v28, v29
	v_max3_f32 v68, v68, v30, v31
	v_max3_f32 v68, v68, v32, v33
	v_max3_f32 v68, v68, v34, v35
	v_max3_f32 v68, v68, v36, v37
	v_max3_f32 v68, v68, v38, v39
	v_max3_f32 v68, v68, v40, v41
	v_max3_f32 v68, v68, v42, v43
	v_max3_f32 v76, v68, v44, v45
	v_lshl_add_u64 v[68:69], v[50:51], 0, s[28:29]
	s_mov_b64 s[28:29], 0xa000
	v_lshl_add_u64 v[70:71], s[42:43], 0, v[68:69]
	v_lshl_add_u64 v[50:51], v[50:51], 0, s[28:29]
	v_lshl_add_u64 v[68:69], s[38:39], 0, v[68:69]
	v_lshl_add_u64 v[72:73], s[42:43], 0, v[50:51]
	global_load_dwordx4 v[128:131], v[70:71], off
	global_load_dwordx4 v[136:139], v[72:73], off
	v_lshl_add_u64 v[50:51], s[38:39], 0, v[50:51]
	global_load_dwordx4 v[132:135], v[68:69], off
	global_load_dwordx4 v[140:143], v[50:51], off
	v_max3_f32 v50, v76, v46, v47
	v_mov_b32_e32 v51, v50
	s_nop 1
	v_permlane32_swap_b32_e32 v50, v51
	v_max_f32_e32 v51, v51, v51
	v_max_f32_e32 v50, v50, v50
	v_max_f32_e32 v50, v50, v51
	v_add_f32_e32 v51, 0x7149f2ca, v50
	v_max_f32_e32 v50, 0xf149f2ca, v50
	v_cmp_ge_f32_e32 vcc, s4, v51
	v_sub_f32_e32 v51, 0xf149f2ca, v50
	v_mul_f32_e32 v51, 0x3e0293ee, v51
	v_exp_f32_e32 v51, v51
	s_cmp_eq_u64 vcc, exec
	s_cselect_b64 vcc, -1, 0
	s_addk_i32 s3, 0x4000
	v_cndmask_b32_e64 v201, v51, 1.0, vcc
	v_mov_b32_e32 v51, 0xf149f2ca
	v_cndmask_b32_e32 v168, v50, v51, vcc
	v_mul_f32_e32 v50, 0xbe0293ee, v168
	v_fmamk_f32 v16, v16, 0x3e0293ee, v50
	v_exp_f32_e32 v161, v16
	v_fmamk_f32 v16, v17, 0x3e0293ee, v50
	v_exp_f32_e32 v175, v16
	v_fmamk_f32 v16, v18, 0x3e0293ee, v50
	v_exp_f32_e32 v162, v16
	v_fmamk_f32 v16, v19, 0x3e0293ee, v50
	v_exp_f32_e32 v205, v16
	v_fmamk_f32 v16, v20, 0x3e0293ee, v50
	v_exp_f32_e32 v174, v16
	v_fmamk_f32 v16, v21, 0x3e0293ee, v50
	v_exp_f32_e32 v214, v16
	v_fmamk_f32 v16, v22, 0x3e0293ee, v50
	v_exp_f32_e32 v163, v16
	v_fmamk_f32 v16, v23, 0x3e0293ee, v50
	v_exp_f32_e32 v173, v16
	v_fmamk_f32 v16, v24, 0x3e0293ee, v50
	v_exp_f32_e32 v164, v16
	v_fmamk_f32 v16, v25, 0x3e0293ee, v50
	v_exp_f32_e32 v171, v16
	v_fmamk_f32 v16, v26, 0x3e0293ee, v50
	v_exp_f32_e32 v165, v16
	v_fmamk_f32 v16, v27, 0x3e0293ee, v50
	v_exp_f32_e32 v172, v16
	v_fmamk_f32 v16, v28, 0x3e0293ee, v50
	v_exp_f32_e32 v166, v16
	v_fmamk_f32 v16, v29, 0x3e0293ee, v50
	v_pk_fma_f32 v[144:145], v[46:47], s[22:23], v[50:51] op_sel_hi:[1,0,0]
	v_pk_fma_f32 v[150:151], v[44:45], s[22:23], v[50:51] op_sel_hi:[1,0,0]
	v_pk_fma_f32 v[154:155], v[42:43], s[22:23], v[50:51] op_sel_hi:[1,0,0]
	v_pk_fma_f32 v[146:147], v[40:41], s[22:23], v[50:51] op_sel_hi:[1,0,0]
	v_pk_fma_f32 v[148:149], v[38:39], s[22:23], v[50:51] op_sel_hi:[1,0,0]
	v_pk_fma_f32 v[152:153], v[36:37], s[22:23], v[50:51] op_sel_hi:[1,0,0]
	v_pk_fma_f32 v[156:157], v[34:35], s[22:23], v[50:51] op_sel_hi:[1,0,0]
	v_pk_fma_f32 v[158:159], v[32:33], s[22:23], v[50:51] op_sel_hi:[1,0,0]
	v_exp_f32_e32 v169, v16
	v_fmamk_f32 v16, v30, 0x3e0293ee, v50
	v_fmac_f32_e32 v50, 0x3e0293ee, v31
	v_add_u32_e32 v187, s3, v75
	v_readlane_b32 s3, v253, 29
	v_exp_f32_e32 v167, v16
	v_exp_f32_e32 v170, v50
	v_and_b32_e32 v16, 15, v74
	s_add_u32 s0, s3, s0
	v_readlane_b32 s3, v253, 30
	s_waitcnt vmcnt(4)
	v_lshl_or_b32 v48, v16, 4, v48
	s_addc_u32 s1, s3, s1
	v_mov_b64_e32 v[12:13], s[84:85]
	s_waitcnt vmcnt(7)
	ds_write_b128 v191, v[52:55] offset:16384
	s_waitcnt vmcnt(6)
	ds_write_b128 v192, v[56:59] offset:16384
	s_waitcnt vmcnt(5)
	ds_write_b128 v189, v[60:63] offset:49152
	s_waitcnt vmcnt(4)
	ds_write_b128 v190, v[64:67] offset:49152
	v_lshl_add_u64 v[180:181], s[0:1], 0, v[48:49]
	v_mov_b64_e32 v[62:63], v[14:15]
	v_mov_b64_e32 v[46:47], v[14:15]
	v_mov_b64_e32 v[30:31], v[14:15]
	v_readlane_b32 s84, v252, 4
	v_cmp_gt_u32_e64 s[38:39], 32, v177
	v_mov_b64_e32 v[60:61], v[12:13]
	v_mov_b64_e32 v[58:59], v[10:11]
	v_mov_b64_e32 v[56:57], v[8:9]
	v_mov_b64_e32 v[54:55], v[6:7]
	v_mov_b64_e32 v[52:53], v[4:5]
	v_mov_b64_e32 v[50:51], v[2:3]
	v_mov_b64_e32 v[48:49], v[0:1]
	v_mov_b64_e32 v[44:45], v[12:13]
	v_mov_b64_e32 v[42:43], v[10:11]
	v_mov_b64_e32 v[40:41], v[8:9]
	v_mov_b64_e32 v[38:39], v[6:7]
	v_mov_b64_e32 v[36:37], v[4:5]
	v_mov_b64_e32 v[34:35], v[2:3]
	v_mov_b64_e32 v[32:33], v[0:1]
	v_mov_b64_e32 v[28:29], v[12:13]
	v_mov_b64_e32 v[26:27], v[10:11]
	v_mov_b64_e32 v[24:25], v[8:9]
	v_mov_b64_e32 v[22:23], v[6:7]
	v_mov_b64_e32 v[20:21], v[4:5]
	v_mov_b64_e32 v[18:19], v[2:3]
	v_mov_b64_e32 v[16:17], v[0:1]
	v_readlane_b32 s85, v252, 5
	v_readlane_b32 s86, v252, 6
	s_mov_b32 s74, 0x7f800000
	s_mov_b32 s75, 0x2b000
	s_mov_b64 s[78:79], 0x800
	s_movk_i32 s77, 0x1ff
	s_waitcnt lgkmcnt(0)
	s_barrier
; #define SBAR() __builtin_amdgcn_sched_barrier(0)
; #define SWAIT() do { if constexpr (SDEPTH == 2) asm volatile("s_waitcnt vmcnt(4)" ::: "memory"); else asm volatile("s_waitcnt vmcnt(0)" ::: "memory"); } while (0)
; template <typename TQ>
; __device__ __forceinline__ void attn_dense_body(const TQ* __restrict__ Qb, const bf16* __restrict__ Kh, const bf16* __restrict__ Vh,
;                                                 unsigned short* __restrict__ Ob, int seq, char* lds) {
;     ...
;   SWAIT(); SWRITE(1, SO); __syncthreads();
;   for (int j = 1; j + 1 < NT; j += 2) {
;     SBAR(); qkt(pB0, pB1, (bf16*)((char*)K_lds + SHM_K), qr, r32, hi);
	v_readlane_b32 s87, v252, 7
	s_waitcnt vmcnt(0)
	v_add_u32_e32 v136, 0x10000, v189
	v_add_u32_e32 v137, 0x10000, v190
	ds_write_b128 v136, v[132:135] offset:32768
	ds_write_b128 v137, v[140:143] offset:32768
	v_lshrrev_b32_e32 v138, 6, v211
	v_lshrrev_b32_e32 v139, 4, v246
	v_lshl_add_u32 v139, v138, 3, v139
	v_and_b32_e32 v129, 15, v246
	v_and_b32_e32 v128, 7, v139
	v_xor_b32_e32 v129, v129, v128
	v_lshlrev_b32_e32 v129, 4, v129
	v_lshl_add_u32 v128, v139, 8, v129
	v_xor_b32_e32 v129, 64, v129
	v_add_u32_e32 v139, 4, v139
	v_lshl_add_u32 v129, v139, 8, v129
	s_nop 1
	v_and_b32_e32 v136, 6, v138
	v_lshlrev_b32_e32 v136, 3, v136
	v_bfe_u32 v137, v246, 2, 2
	v_add_u32_e32 v136, v136, v137
	v_bfe_u32 v137, v246, 4, 1
	v_lshl_add_u32 v136, v137, 3, v136
	v_and_b32_e32 v137, 1, v138
	v_lshl_add_u32 v136, v137, 2, v136
	v_lshlrev_b32_e32 v136, 8, v136
	v_bfe_u32 v137, v246, 5, 1
	v_lshl_add_u32 v136, v137, 6, v136
	v_and_b32_e32 v137, 3, v246
	v_lshl_add_u32 v130, v137, 4, v136
	v_add_u32_e32 v131, 0x80, v130
	v_readfirstlane_b32 s5, v211
	s_nop 3
	s_lshr_b32 s5, s5, 6
	s_lshl_b32 s5, s5, 11
	s_mov_b32 s28, 0
	s_mov_b32 s29, 0x10000
	s_add_u32 s6, s6, 0xc000
	s_addc_u32 s7, s7, 0
	s_add_u32 s68, s68, 0x8000
	s_addc_u32 s69, s69, 0
	s_add_i32 m0, s5, 0x1c000
	s_nop 0
	global_load_lds_dwordx4 v128, s[6:7]
	s_add_i32 m0, s5, 0x1c400
	s_nop 0
	global_load_lds_dwordx4 v129, s[6:7]
	s_add_i32 m0, s5, 0x10000
	s_nop 0
	global_load_lds_dwordx4 v130, s[68:69]
	s_add_i32 m0, s5, 0x10400
	s_nop 0
	global_load_lds_dwordx4 v131, s[68:69]
	s_add_u32 s6, s6, 0x4000
	s_addc_u32 s7, s7, 0
	s_add_u32 s68, s68, 0x4000
	s_addc_u32 s69, s69, 0
	s_cmp_ge_u32 s5, 0x2000
	s_cbranch_scc0 .Latt_skipE0
	s_waitcnt lgkmcnt(0)
	s_barrier
	s_setprio 1

; #define SBAR() __builtin_amdgcn_sched_barrier(0)
; #define RESC(a) do { if (__any((a) < 1.f)) { if (hi == 0) al_l[r32] = (a); asm volatile("s_waitcnt lgkmcnt(0)" ::: "memory"); \
;     for (int d = 0; d < 4; ++d) for (int r = 0; r < 16; ++r) o[d][r] *= al_l[crow(r, hi)]; } } while (0)
; template <typename TQ>
; __device__ __forceinline__ void attn_dense_body(const TQ* __restrict__ Qb, const bf16* __restrict__ Kh, const bf16* __restrict__ Vh,
;                                                 unsigned short* __restrict__ Ob, int seq, char* lds) {
;     ...
;   SBAR(); qkt(pB0, pB1, (bf16*)((char*)K_lds + SHM_K), qr, r32, hi);
;   finishSM(pA0, pA1, alA, l_reg, pa0, pa1, pa2, pa3); SBAR();
;   pv_d0(o, vb0, pa0, pa1, pa2, pa3); partialSM(pB0, pB1, m_reg, mnB, alB);
;   __syncthreads(); RESC(alB);
;   finishSM(pB0, pB1, alB, l_reg, pa0, pa1, pa2, pa3); SBAR();
;   pv_d0(o, vb0 + (int)SHM_V, pa0, pa1, pa2, pa3);
.LBB0_88:
	s_setprio 0
	ds_read_b128 v[64:67], v193 offset:49152
	ds_read_b128 v[68:71], v193 offset:57344
	s_waitcnt lgkmcnt(1)
	v_mfma_f32_32x32x16_bf16 v[80:95], v[64:67], v[112:115], 0
	s_waitcnt lgkmcnt(0)
	v_mfma_f32_32x32x16_bf16 v[64:79], v[68:71], v[112:115], 0
	ds_read_b128 v[112:115], v198 offset:49152
	ds_read_b128 v[128:131], v198 offset:57344
	s_waitcnt lgkmcnt(1)
	v_mfma_f32_32x32x16_bf16 v[80:95], v[112:115], v[108:111], v[80:95]
	s_waitcnt lgkmcnt(0)
	v_mfma_f32_32x32x16_bf16 v[64:79], v[128:131], v[108:111], v[64:79]
	ds_read_b128 v[108:111], v197 offset:49152
	ds_read_b128 v[112:115], v197 offset:57344
	s_waitcnt lgkmcnt(1)
	v_mfma_f32_32x32x16_bf16 v[80:95], v[108:111], v[120:123], v[80:95]
	s_waitcnt lgkmcnt(0)
	v_mfma_f32_32x32x16_bf16 v[64:79], v[112:115], v[120:123], v[64:79]
	ds_read_b128 v[108:111], v196 offset:49152
	ds_read_b128 v[112:115], v196 offset:57344
	v_exp_f32_e32 v120, v144
	v_exp_f32_e32 v121, v145
	s_waitcnt lgkmcnt(1)
	v_mfma_f32_32x32x16_bf16 v[80:95], v[108:111], v[124:127], v[80:95]
	s_waitcnt lgkmcnt(0)
	v_mfma_f32_32x32x16_bf16 v[64:79], v[112:115], v[124:127], v[64:79]
	ds_read_b128 v[108:111], v194 offset:49152
	ds_read_b128 v[112:115], v194 offset:57344
	s_waitcnt lgkmcnt(1)
	v_mfma_f32_32x32x16_bf16 v[80:95], v[108:111], v[116:119], v[80:95]
	s_waitcnt lgkmcnt(0)
	v_mfma_f32_32x32x16_bf16 v[64:79], v[112:115], v[116:119], v[64:79]
	ds_read_b128 v[108:111], v195 offset:49152
	ds_read_b128 v[112:115], v195 offset:57344
	v_exp_f32_e32 v116, v154
	v_exp_f32_e32 v117, v155
	v_exp_f32_e32 v118, v150
	v_exp_f32_e32 v119, v151
	s_waitcnt lgkmcnt(1)
	v_mfma_f32_32x32x16_bf16 v[80:95], v[108:111], v[104:107], v[80:95]
	s_waitcnt lgkmcnt(0)
	v_mfma_f32_32x32x16_bf16 v[64:79], v[112:115], v[104:107], v[64:79]
	ds_read_b128 v[104:107], v200 offset:49152
	ds_read_b128 v[108:111], v200 offset:57344
	v_exp_f32_e32 v112, v148
	v_exp_f32_e32 v113, v149
	v_exp_f32_e32 v114, v146
	v_exp_f32_e32 v115, v147
	s_waitcnt lgkmcnt(1)
	v_mfma_f32_32x32x16_bf16 v[80:95], v[104:107], v[100:103], v[80:95]
	s_waitcnt lgkmcnt(0)
	v_mfma_f32_32x32x16_bf16 v[64:79], v[108:111], v[100:103], v[64:79]
	ds_read_b128 v[100:103], v199 offset:49152
	ds_read_b128 v[104:107], v199 offset:57344
	v_exp_f32_e32 v108, v156
	v_exp_f32_e32 v109, v157
	v_exp_f32_e32 v110, v152
	v_exp_f32_e32 v111, v153
	s_waitcnt lgkmcnt(1)
	v_mfma_f32_32x32x16_bf16 v[80:95], v[100:103], v[96:99], v[80:95]
	s_waitcnt lgkmcnt(0)
	v_mfma_f32_32x32x16_bf16 v[64:79], v[104:107], v[96:99], v[64:79]
	v_add_f32_e32 v96, 0, v161
	v_add_f32_e32 v96, v175, v96
	v_add_f32_e32 v96, v162, v96
	v_add_f32_e32 v96, v205, v96
	v_add_f32_e32 v96, v174, v96
	v_add_f32_e32 v96, v214, v96
	v_add_f32_e32 v96, v163, v96
	v_add_f32_e32 v96, v173, v96
	v_add_f32_e32 v96, v164, v96
	v_add_f32_e32 v96, v171, v96
	v_add_f32_e32 v96, v165, v96
	v_add_f32_e32 v96, v172, v96
	v_exp_f32_e32 v106, v158
	v_add_f32_e32 v96, v166, v96
	v_exp_f32_e32 v107, v159
	v_add_f32_e32 v96, v169, v96
	v_add_f32_e32 v96, v167, v96
	v_add_f32_e32 v96, v170, v96
	v_add_f32_e32 v96, v106, v96
	v_add_f32_e32 v96, v107, v96
	v_add_f32_e32 v96, v108, v96
	v_add_f32_e32 v96, v109, v96
	v_add_f32_e32 v96, v110, v96
	v_add_f32_e32 v96, v111, v96
	v_add_f32_e32 v96, v112, v96
	v_add_f32_e32 v96, v113, v96
	v_add_f32_e32 v96, v114, v96
	v_add_f32_e32 v96, v115, v96
	v_add_f32_e32 v96, v116, v96
	v_add_f32_e32 v96, v117, v96
	v_add_f32_e32 v96, v118, v96
	v_add_f32_e32 v96, v119, v96
	v_add_f32_e32 v96, v120, v96
	v_add_f32_e32 v100, v121, v96
	v_mov_b32_e32 v101, v100
	v_cvt_pk_bf16_f32 v96, v161, v175
	v_cvt_pk_bf16_f32 v97, v162, v205
	v_cvt_pk_bf16_f32 v98, v174, v214
	v_cvt_pk_bf16_f32 v99, v163, v173
	s_nop 1
	v_permlane32_swap_b32_e32 v100, v101
	v_permlane32_swap_b32_e32 v96, v98
	v_permlane32_swap_b32_e32 v97, v99
	v_cvt_pk_bf16_f32 v102, v164, v171
	v_cvt_pk_bf16_f32 v103, v165, v172
	v_cvt_pk_bf16_f32 v104, v166, v169
	v_cvt_pk_bf16_f32 v105, v167, v170
	v_cvt_pk_bf16_f32 v106, v106, v107
	v_cvt_pk_bf16_f32 v107, v108, v109
	v_cvt_pk_bf16_f32 v108, v110, v111
	v_cvt_pk_bf16_f32 v109, v112, v113
	v_cvt_pk_bf16_f32 v110, v114, v115
	v_cvt_pk_bf16_f32 v111, v116, v117
	v_cvt_pk_bf16_f32 v112, v118, v119
	v_cvt_pk_bf16_f32 v113, v120, v121
	s_nop 0
	v_permlane32_swap_b32_e32 v102, v104
	v_permlane32_swap_b32_e32 v103, v105
	v_permlane32_swap_b32_e32 v106, v108
	v_permlane32_swap_b32_e32 v107, v109
	v_permlane32_swap_b32_e32 v110, v112
	v_permlane32_swap_b32_e32 v111, v113
	ds_read_b64_tr_b16 v[114:115], v188 offset:0
	ds_read_b64_tr_b16 v[116:117], v188 offset:0x800
	ds_read_b64_tr_b16 v[118:119], v188 offset:0x1000
	ds_read_b64_tr_b16 v[120:121], v188 offset:0x1800
	ds_read_b64_tr_b16 v[122:123], v188 offset:0x2000
	ds_read_b64_tr_b16 v[124:125], v188 offset:0x2800
	ds_read_b64_tr_b16 v[126:127], v188 offset:0x3000
	ds_read_b64_tr_b16 v[128:129], v188 offset:0x3800
	s_waitcnt lgkmcnt(0)
; #define SBAR() __builtin_amdgcn_sched_barrier(0)
; __device__ __forceinline__ void partialSM(f32x16& p0, f32x16& p1, float& m_reg, float& mn, float& alpha) {
;   constexpr float C = SCALE * 1.4426950408889634f;
;   float pmax = p0[0]; for (int r = 1; r < 16; ++r) pmax = fmaxf(pmax, p0[r]); for (int r = 0; r < 16; ++r) pmax = fmaxf(pmax, p1[r]);
;   { auto rr = __builtin_amdgcn_permlane32_swap(__float_as_uint(pmax), __float_as_uint(pmax), false, false);
;     pmax = fmaxf(__uint_as_float(rr[0]), __uint_as_float(rr[1])); }
;   if (__builtin_expect(__all(pmax - m_reg <= THR / SCALE), 1)) { mn = m_reg; alpha = 1.f; }
;   else { mn = fmaxf(m_reg, pmax); alpha = __builtin_amdgcn_exp2f((m_reg - mn) * C); m_reg = mn; }
; template <int D0> __device__ __forceinline__ void pv_one(f32x16& od, int vb, bf16x8 pa0, bf16x8 pa1, bf16x8 pa2, bf16x8 pa3) {
;   const s16x4 l0 = tr_read<v_rd_off(D0, 0, 0)>(vb), h0 = tr_read<v_rd_off(D0, 0, 1)>(vb), l1 = tr_read<v_rd_off(D0, 1, 0)>(vb), h1 = tr_read<v_rd_off(D0, 1, 1)>(vb);
;   const s16x4 l2 = tr_read<v_rd_off(D0, 2, 0)>(vb), h2 = tr_read<v_rd_off(D0, 2, 1)>(vb), l3 = tr_read<v_rd_off(D0, 3, 0)>(vb), h3 = tr_read<v_rd_off(D0, 3, 1)>(vb);
;   asm volatile("s_waitcnt lgkmcnt(0)" ::: "memory"); SBAR();
;     ...
;   od = __builtin_amdgcn_mfma_f32_32x32x16_bf16(pa0, PK(l0, h0), od, 0, 0, 0);
;   od = __builtin_amdgcn_mfma_f32_32x32x16_bf16(pa1, PK(l1, h1), od, 0, 0, 0);
;   od = __builtin_amdgcn_mfma_f32_32x32x16_bf16(pa2, PK(l2, h2), od, 0, 0, 0);
;   od = __builtin_amdgcn_mfma_f32_32x32x16_bf16(pa3, PK(l3, h3), od, 0, 0, 0);
;     ...
; }
; __device__ __forceinline__ void pv_d0(f32x16* o, int vb, bf16x8 pa0, bf16x8 pa1, bf16x8 pa2, bf16x8 pa3) {
;   pv_one<0>(o[0], vb, pa0, pa1, pa2, pa3); pv_one<1>(o[1], vb, pa0, pa1, pa2, pa3); pv_one<2>(o[2], vb, pa0, pa1, pa2, pa3); pv_one<3>(o[3], vb, pa0, pa1, pa2, pa3);
	s_nop 0
	v_mfma_f32_32x32x16_bf16 v[0:15], v[96:99], v[114:117], v[0:15]
	ds_read_b64_tr_b16 v[114:115], v188 offset:0x200
	ds_read_b64_tr_b16 v[116:117], v188 offset:0xa00
	v_mfma_f32_32x32x16_bf16 v[0:15], v[102:105], v[118:121], v[0:15]
	ds_read_b64_tr_b16 v[118:119], v188 offset:0x1200
	ds_read_b64_tr_b16 v[120:121], v188 offset:0x1a00
	v_mfma_f32_32x32x16_bf16 v[0:15], v[106:109], v[122:125], v[0:15]
	ds_read_b64_tr_b16 v[122:123], v188 offset:0x2200
	ds_read_b64_tr_b16 v[124:125], v188 offset:0x2a00
	v_mfma_f32_32x32x16_bf16 v[0:15], v[110:113], v[126:129], v[0:15]
	ds_read_b64_tr_b16 v[126:127], v188 offset:0x3200
	ds_read_b64_tr_b16 v[128:129], v188 offset:0x3a00
	s_waitcnt lgkmcnt(0)
	v_mfma_f32_32x32x16_bf16 v[48:63], v[96:99], v[114:117], v[48:63]
	ds_read_b64_tr_b16 v[114:115], v188 offset:0x400
	ds_read_b64_tr_b16 v[116:117], v188 offset:0xc00
	v_mfma_f32_32x32x16_bf16 v[48:63], v[102:105], v[118:121], v[48:63]
	ds_read_b64_tr_b16 v[118:119], v188 offset:0x1400
	ds_read_b64_tr_b16 v[120:121], v188 offset:0x1c00
	v_mfma_f32_32x32x16_bf16 v[48:63], v[106:109], v[122:125], v[48:63]
	ds_read_b64_tr_b16 v[122:123], v188 offset:0x2400
	ds_read_b64_tr_b16 v[124:125], v188 offset:0x2c00
	v_mfma_f32_32x32x16_bf16 v[48:63], v[110:113], v[126:129], v[48:63]
	ds_read_b64_tr_b16 v[126:127], v188 offset:0x3400
	ds_read_b64_tr_b16 v[128:129], v188 offset:0x3c00
	s_waitcnt lgkmcnt(0)
	v_mfma_f32_32x32x16_bf16 v[32:47], v[96:99], v[114:117], v[32:47]
	ds_read_b64_tr_b16 v[114:115], v188 offset:0x600
	ds_read_b64_tr_b16 v[116:117], v188 offset:0xe00
	v_mfma_f32_32x32x16_bf16 v[32:47], v[102:105], v[118:121], v[32:47]
	ds_read_b64_tr_b16 v[118:119], v188 offset:0x1600
	ds_read_b64_tr_b16 v[120:121], v188 offset:0x1e00
	v_mfma_f32_32x32x16_bf16 v[32:47], v[106:109], v[122:125], v[32:47]
	ds_read_b64_tr_b16 v[122:123], v188 offset:0x2600
	ds_read_b64_tr_b16 v[124:125], v188 offset:0x2e00
	v_mfma_f32_32x32x16_bf16 v[32:47], v[110:113], v[126:129], v[32:47]
	ds_read_b64_tr_b16 v[126:127], v188 offset:0x3600
	ds_read_b64_tr_b16 v[128:129], v188 offset:0x3e00
	s_waitcnt lgkmcnt(0)
	v_mfma_f32_32x32x16_bf16 v[16:31], v[96:99], v[114:117], v[16:31]
	v_max_f32_e32 v96, v81, v81
	v_max_f32_e32 v97, v80, v80
	v_max_f32_e32 v96, v97, v96
	v_max3_f32 v96, v96, v82, v83
	v_max3_f32 v96, v96, v84, v85
	v_max3_f32 v96, v96, v86, v87
	v_max3_f32 v96, v96, v88, v89
	v_max3_f32 v96, v96, v90, v91
	v_max3_f32 v96, v96, v92, v93
	v_mfma_f32_32x32x16_bf16 v[16:31], v[102:105], v[118:121], v[16:31]
	v_max3_f32 v96, v96, v94, v95
	v_max3_f32 v96, v96, v64, v65
	v_max3_f32 v96, v96, v66, v67
	v_max3_f32 v96, v96, v68, v69
	v_max3_f32 v96, v96, v70, v71
	v_max3_f32 v96, v96, v72, v73
	v_max3_f32 v96, v96, v74, v75
	v_max3_f32 v96, v96, v76, v77
	v_mfma_f32_32x32x16_bf16 v[16:31], v[106:109], v[122:125], v[16:31]
	v_max3_f32 v96, v96, v78, v79
	v_mov_b32_e32 v97, v96
	s_nop 1
	v_permlane32_swap_b32_e32 v96, v97
	v_max_f32_e32 v97, v97, v97
	v_max_f32_e32 v96, v96, v96
	v_max_f32_e32 v96, v96, v97
	v_sub_f32_e32 v97, v96, v168
	v_cmp_ge_f32_e32 vcc, s4, v97
	v_max_f32_e32 v97, v168, v168
	v_max_f32_e32 v97, v97, v96
	v_mfma_f32_32x32x16_bf16 v[16:31], v[110:113], v[126:129], v[16:31]
	v_sub_f32_e32 v96, v168, v97
	v_mul_f32_e32 v96, 0x3e0293ee, v96
	v_exp_f32_e32 v96, v96
	s_cmp_eq_u64 vcc, exec
	s_cselect_b64 s[0:1], -1, 0
	v_cndmask_b32_e64 v96, v96, 1.0, s[0:1]
	v_cmp_gt_f32_e32 vcc, 1.0, v96
	s_waitcnt vmcnt(0)
	s_barrier
	s_cbranch_vccz .LBB0_92
	s_mov_b64 s[42:43], exec
	s_and_b64 s[28:29], s[42:43], s[38:39]
	v_mov_b64_e32 v[228:229], v[242:243]
	v_mov_b64_e32 v[230:231], v[218:219]
	s_mov_b64 exec, s[28:29]
	ds_write_b32 v185, v96 offset:128
	s_or_b64 exec, exec, s[42:43]
	s_waitcnt lgkmcnt(0)
	v_add_u32_e32 v98, v184, v208
	ds_read_b128 v[102:105], v98 offset:224
	ds_read_b128 v[106:109], v98 offset:192
	ds_read_b128 v[110:113], v98 offset:160
	ds_read_b128 v[114:117], v98 offset:128
	s_waitcnt lgkmcnt(3)
	v_pk_mul_f32 v[12:13], v[12:13], v[102:103]
	s_waitcnt lgkmcnt(2)
	v_pk_mul_f32 v[8:9], v[8:9], v[106:107]
	s_waitcnt lgkmcnt(1)
	v_pk_mul_f32 v[4:5], v[4:5], v[110:111]
	v_pk_mul_f32 v[14:15], v[14:15], v[104:105]
	v_pk_mul_f32 v[10:11], v[10:11], v[108:109]
	v_pk_mul_f32 v[6:7], v[6:7], v[112:113]
	s_waitcnt lgkmcnt(0)
	v_pk_mul_f32 v[2:3], v[2:3], v[116:117]
	v_pk_mul_f32 v[0:1], v[0:1], v[114:115]
	v_pk_mul_f32 v[60:61], v[60:61], v[102:103]
	v_pk_mul_f32 v[56:57], v[56:57], v[106:107]
	v_pk_mul_f32 v[52:53], v[52:53], v[110:111]
	v_pk_mul_f32 v[62:63], v[62:63], v[104:105]
	v_pk_mul_f32 v[58:59], v[58:59], v[108:109]
	v_pk_mul_f32 v[54:55], v[54:55], v[112:113]
	v_pk_mul_f32 v[50:51], v[50:51], v[116:117]
	v_pk_mul_f32 v[48:49], v[48:49], v[114:115]
	v_pk_mul_f32 v[44:45], v[44:45], v[102:103]
	v_pk_mul_f32 v[40:41], v[40:41], v[106:107]
	v_pk_mul_f32 v[36:37], v[36:37], v[110:111]
	v_pk_mul_f32 v[46:47], v[46:47], v[104:105]
	v_pk_mul_f32 v[42:43], v[42:43], v[108:109]
	v_pk_mul_f32 v[38:39], v[38:39], v[112:113]
	v_pk_mul_f32 v[34:35], v[34:35], v[116:117]
	v_pk_mul_f32 v[32:33], v[32:33], v[114:115]
	v_pk_mul_f32 v[28:29], v[28:29], v[102:103]
	v_pk_mul_f32 v[24:25], v[24:25], v[106:107]
	v_pk_mul_f32 v[20:21], v[20:21], v[110:111]
	v_pk_mul_f32 v[30:31], v[30:31], v[104:105]
	v_pk_mul_f32 v[26:27], v[26:27], v[108:109]
	v_pk_mul_f32 v[22:23], v[22:23], v[112:113]
	v_pk_mul_f32 v[18:19], v[18:19], v[116:117]
	v_pk_mul_f32 v[16:17], v[16:17], v[114:115]
	s_branch .LBB0_93
